# attention unit order: 16 CUs per (b,h), two heads of one batch per XCD round
# speedup vs baseline: 1.0118x; 1.0118x over previous
; #define LAS __attribute__((address_space(3)))
; #define GAS __attribute__((address_space(1)))
; __device__ __forceinline__ int kap(int m) { return (m & ~12) | ((m & 4) << 1) | ((m & 8) >> 1); }
; __device__ __forceinline__ void unit(const Ctx& F, int b, int h, int qb, const bf16_t* Q, const bf16_t* Kg, const bf16_t* VT, bf16_t* O, float lam) {
;     LAS unsigned char* lds = F.lds; const int lane = F.lane, wid = F.wave, r32 = lane & 31, hi = lane >> 5, rg = wid >> 1, s = wid & 1;
;     const size_t tok0 = (size_t)b * SEQ; const int q0 = qb * 128 + rg * 32;
;     bf16x8 qf[4];
;     { const bf16_t* qp = Q + (tok0 + q0 + r32) * D + h * 128 + s * 64 + hi * 8;
; #pragma unroll
;       for (int d0 = 0; d0 < 4; ++d0) qf[d0] = *(const GAS bf16x8*)(qp + d0 * 16); }
;     f32x16 o[4];
; #pragma unroll
;     for (int db = 0; db < 4; ++db)
; #pragma unroll
;         for (int r = 0; r < 16; ++r) o[db][r] = 0.f;
;     float mrun = -1e30f, lrun = 0.f;
;     const int NT = qb * 2 + 2, cq = qb * 2 + (rg >> 1);
;     const bf16_t* ksrc[2]; const bf16_t* vsrc[2];
; #pragma unroll
;     for (int i = 0; i < 2; ++i) { const int kr = 4 * (2 * wid + i) + (lane >> 4), ks = (lane & 15) ^ (kr & 15); ksrc[i] = Kg + (tok0 + kr) * D + h * 128 + ks * 8;
;         const int vr = 8 * (2 * wid + i) + (lane >> 3), vs = (lane & 7) ^ ((vr >> 1) & 7); vsrc[i] = VT + (size_t)(h * 128 + vr) * T + tok0 + vs * 8; }
;     ...
;     const int krow = kap(r32);
;     int kad[4], vad[4];
; #pragma unroll
;     for (int i = 0; i < 4; ++i) { kad[i] = krow * 256 + (((s * 8 + i * 2 + hi) ^ (krow & 15)) << 4); vad[i] = r32 * 128 + (((i * 2 + hi) ^ ((r32 >> 1) & 7)) << 4); }
;     bf16x8 pf[4];
;     ...
;     ATT_DMA(0, 0); ATT_DMA(1, BUF);
; __device__ __forceinline__ void phase(const Ctx& F, const bf16_t* Q, const bf16_t* Kg, const bf16_t* VT, bf16_t* O, float lam) {
;     for (int v = F.bid; v < 256; v += F.G) {
;         const int xcd = v & 7, ci = v >> 3;
; #pragma nounroll
;         for (int i = 0; i < 8; ++i) { const int bh = xcd * 16 + (i >> 1) * 4 + (ci >> 3), p = ci & 7; const int qb = (i & 1) ? 15 - p : p; unit(F, bh >> 3, bh & 7, qb, Q, Kg, VT, O, lam); }
;     }
; }
.LBB0_234:
	s_lshr_b32 s15, s34, 7
	s_add_i32 s16, s42, s15
	s_and_b32 s15, s16, 7
	s_lshl_b32 s74, s15, 8
	s_lshl_b32 s45, s15, 7
	s_add_i32 s15, s16, s35
	s_bfe_u32 s98, s34, 0x40003
	s_xor_b32 s99, s98, 15
	s_bitcmp0_b32 s43, 0
	s_cselect_b32 s75, s98, s99
	s_ashr_i32 s26, s15, 3
	s_lshl_b32 s16, s75, 7
	s_ashr_i32 s27, s26, 31
	s_add_i32 s16, s16, s8
	s_lshl_b64 s[50:51], s[26:27], 11
	s_ashr_i32 s17, s16, 31
	s_add_u32 s16, s50, s16
	s_addc_u32 s17, s51, s17
	v_mov_b32_e32 v1, s17
	v_or_b32_e32 v0, s16, v112
	s_lshl_b32 s15, s15, 7
	v_lshlrev_b64 v[0:1], 11, v[0:1]
	s_and_b32 s44, s15, 0x380
	v_lshl_add_u64 v[0:1], s[24:25], 0, v[0:1]
	s_lshl_b32 s52, s44, 1
	s_mov_b32 s53, s88
	v_lshl_add_u64 v[0:1], v[0:1], 0, s[52:53]
	s_mov_b32 s15, s88
	v_lshl_add_u64 v[0:1], v[0:1], 0, s[14:15]
	s_lshl_b32 s15, s75, 1
	v_lshl_add_u64 v[0:1], v[0:1], 0, v[156:157]
	s_add_u32 s52, s0, s52
	global_load_dwordx4 v[96:99], v[0:1], off
	global_load_dwordx4 v[100:103], v[0:1], off offset:32
	global_load_dwordx4 v[104:107], v[0:1], off offset:64
	global_load_dwordx4 v[108:111], v[0:1], off offset:96
	s_addc_u32 s53, s1, 0
	s_lshl_b64 s[54:55], s[26:27], 12
	v_lshl_add_u64 v[0:1], s[50:51], 0, v[114:115]
	v_add_u32_e32 v2, s44, v165
	s_add_u32 s72, s4, s54
	v_lshlrev_b64 v[0:1], 11, v[0:1]
	v_ashrrev_i32_e32 v3, 31, v2
	s_addc_u32 s73, s5, s55
	v_lshl_add_u64 v[0:1], s[52:53], 0, v[0:1]
	v_mov_b32_e32 v145, v157
	v_lshlrev_b64 v[2:3], 16, v[2:3]
	v_lshl_add_u64 v[4:5], s[50:51], 0, v[116:117]
	v_add_u32_e32 v6, s44, v172
	s_mov_b32 m0, s28
	v_lshl_add_u64 v[0:1], v[0:1], 0, v[144:145]
	v_lshl_add_u64 v[2:3], s[72:73], 0, v[2:3]
	v_mov_b32_e32 v147, v157
	v_lshlrev_b64 v[4:5], 11, v[4:5]
	v_ashrrev_i32_e32 v7, 31, v6
	v_lshl_add_u64 v[2:3], v[2:3], 0, v[146:147]
	v_lshl_add_u64 v[4:5], s[52:53], 0, v[4:5]
	v_mov_b32_e32 v149, v157
	v_lshlrev_b64 v[6:7], 16, v[6:7]
	global_load_lds_dwordx4 v[0:1], off
	s_add_i32 m0, s28, 0x4000
	v_lshl_add_u64 v[4:5], v[4:5], 0, v[148:149]
	v_lshl_add_u64 v[6:7], s[72:73], 0, v[6:7]
	v_mov_b32_e32 v151, v157
	global_load_lds_dwordx4 v[2:3], off
	s_add_i32 m0, s28, 0x400
	v_lshl_add_u64 v[6:7], v[6:7], 0, v[150:151]
	global_load_lds_dwordx4 v[4:5], off
	s_mov_b32 m0, s29
	v_lshl_add_u64 v[0:1], v[0:1], 0, s[18:19]
	global_load_lds_dwordx4 v[6:7], off
	s_add_i32 m0, s28, 0x8000
	s_lshl_b64 s[26:27], s[26:27], 22
	global_load_lds_dwordx4 v[0:1], off
	v_lshl_add_u64 v[0:1], v[2:3], 0, s[38:39]
	s_add_i32 m0, s28, 0xc000
	v_add_u32_e32 v2, s45, v165
	global_load_lds_dwordx4 v[0:1], off
	v_lshl_add_u64 v[0:1], v[4:5], 0, s[18:19]
	s_mov_b32 m0, s30
	v_ashrrev_i32_e32 v3, 31, v2
	global_load_lds_dwordx4 v[0:1], off
	v_lshl_add_u64 v[0:1], v[6:7], 0, s[38:39]
	s_mov_b32 m0, s31
	v_lshlrev_b64 v[2:3], 16, v[2:3]
	global_load_lds_dwordx4 v[0:1], off
	v_add_u32_e32 v0, s45, v183
	v_ashrrev_i32_e32 v1, 31, v0
	v_lshlrev_b64 v[0:1], 16, v[0:1]
	v_lshl_add_u64 v[0:1], v[136:137], 0, v[0:1]
	v_lshl_add_u64 v[154:155], v[0:1], 0, s[54:55]
	v_lshl_add_u64 v[0:1], v[138:139], 0, v[2:3]
	v_mov_b32_e32 v48, v157
	v_mov_b32_e32 v49, v157
	s_lshl_b32 s53, s75, 16
	s_or_b32 s26, s26, s74
	v_lshl_add_u64 v[168:169], v[0:1], 0, s[54:55]
	v_mov_b32_e32 v50, v157
	v_mov_b32_e32 v51, v157
	v_mov_b32_e32 v52, v157
	v_mov_b32_e32 v53, v157
	v_mov_b32_e32 v54, v157
	v_mov_b32_e32 v55, v157
	v_mov_b32_e32 v56, v157
	v_mov_b32_e32 v57, v157
	v_mov_b32_e32 v58, v157
	v_mov_b32_e32 v59, v157
	v_mov_b32_e32 v60, v157
	v_mov_b32_e32 v61, v157
	v_mov_b32_e32 v62, v157
	v_mov_b32_e32 v63, v157
	v_mov_b64_e32 v[32:33], v[48:49]
	v_mov_b64_e32 v[16:17], v[48:49]
	v_mov_b64_e32 v[0:1], v[48:49]
	s_mov_b32 s45, 1
	s_mov_b32 s50, 2
	s_add_i32 s51, s15, 2
	s_add_i32 s52, s15, s9
	s_add_i32 s53, s53, 0x10000
	v_lshl_add_u64 v[152:153], s[26:27], 0, v[134:135]
	v_lshl_add_u64 v[170:171], s[26:27], 0, v[140:141]
	v_mov_b32_e32 v143, 0
	v_mov_b32_e32 v145, 0xf149f2ca
	s_mov_b32 s54, 0
	v_mov_b64_e32 v[34:35], v[50:51]
	v_mov_b64_e32 v[36:37], v[52:53]
	v_mov_b64_e32 v[38:39], v[54:55]
	v_mov_b64_e32 v[40:41], v[56:57]
	v_mov_b64_e32 v[42:43], v[58:59]
	v_mov_b64_e32 v[44:45], v[60:61]
	v_mov_b64_e32 v[46:47], v[62:63]
	v_mov_b64_e32 v[18:19], v[50:51]
	v_mov_b64_e32 v[20:21], v[52:53]
	v_mov_b64_e32 v[22:23], v[54:55]
	v_mov_b64_e32 v[24:25], v[56:57]
	v_mov_b64_e32 v[26:27], v[58:59]
	v_mov_b64_e32 v[28:29], v[60:61]
	v_mov_b64_e32 v[30:31], v[62:63]
	v_mov_b64_e32 v[2:3], v[50:51]
	v_mov_b64_e32 v[4:5], v[52:53]
	v_mov_b64_e32 v[6:7], v[54:55]
	v_mov_b64_e32 v[8:9], v[56:57]
	v_mov_b64_e32 v[10:11], v[58:59]
	v_mov_b64_e32 v[12:13], v[60:61]
	v_mov_b64_e32 v[14:15], v[62:63]
	s_mov_b32 s55, 0
	s_waitcnt vmcnt(0)
	s_branch .LBB0_237

; __device__ __forceinline__ void unit(const Ctx& F, int b, int h, int qb, const bf16_t* Q, const bf16_t* Kg, const bf16_t* VT, bf16_t* O, float lam) {
;     ...
;     for (int j = 0; j < NT; ++j) {
;         if (j + 1 < NT) asm volatile("s_waitcnt vmcnt(4) lgkmcnt(0)" ::: "memory"); else asm volatile("s_waitcnt vmcnt(0) lgkmcnt(0)" ::: "memory");
;         __builtin_amdgcn_s_barrier(); asm volatile("" ::: "memory");
;         if (j + 2 < NT) ATT_DMA(j + 2, ((j + 2) % 3) * BUF);
;         if (j <= cq) { const int bo = (j % 3) * BUF; ATT_S(bo); ATT_PV(bo); }
.LBB0_239:
	s_andn2_b64 vcc, exec, s[26:27]
	s_cbranch_vccnz .LBB0_241
	s_waitcnt vmcnt(4) lgkmcnt(0)
.LBB0_241:
	s_barrier
	s_add_i32 s26, s45, -1
	s_cmp_ge_u32 s26, s15
	s_cbranch_scc1 .LBB0_243
	s_mul_hi_u32 s27, s50, 0xaaaaaaab
	s_lshr_b32 s27, s27, 1
	s_mul_i32 s27, s27, 0x18000
	s_sub_i32 s27, s54, s27
	s_add_i32 s27, s27, s28
	v_lshl_add_u64 v[64:65], s[48:49], 0, v[152:153]
	s_add_i32 m0, s27, 0x10000
	s_nop 0
	global_load_lds_dwordx4 v[64:65], off
	v_lshl_add_u64 v[64:65], s[48:49], 0, v[168:169]
	s_add_i32 m0, s27, 0x14000
	s_nop 0
	global_load_lds_dwordx4 v[64:65], off
	v_lshl_add_u64 v[64:65], s[48:49], 0, v[170:171]
	s_add_i32 m0, s27, 0x10400
	s_nop 0
	global_load_lds_dwordx4 v[64:65], off
	v_lshl_add_u64 v[64:65], s[48:49], 0, v[154:155]
	s_add_i32 m0, s27, 0x14400
	s_nop 0
	global_load_lds_dwordx4 v[64:65], off
.LBB0_243:
	s_cmp_gt_i32 s26, s52
	s_cbranch_scc1 .LBB0_236
	s_mul_hi_u32 s26, s55, 0xaaaaaaab
	s_lshr_b32 s26, s26, 1
	s_mul_i32 s26, s26, 0x18000
	v_subrev_u32_e32 v72, s26, v179
	v_subrev_u32_e32 v73, s26, v177
	v_subrev_u32_e32 v74, s26, v175
	v_subrev_u32_e32 v64, s26, v173
	v_add_u32_e32 v75, s54, v182
	v_add_u32_e32 v68, v75, v64
	v_add_u32_e32 v74, v75, v74
	v_add_u32_e32 v73, v75, v73
	v_add_u32_e32 v72, v75, v72
	ds_read_b128 v[64:67], v68
	ds_read_b128 v[68:71], v68 offset:8192
	ds_read_b128 v[188:191], v74
	ds_read_b128 v[192:195], v74 offset:8192
	ds_read_b128 v[196:199], v73
	ds_read_b128 v[200:203], v73 offset:8192
	ds_read_b128 v[208:211], v72
	ds_read_b128 v[214:217], v72 offset:8192
	s_waitcnt lgkmcnt(0)
	s_setprio 1
	s_waitcnt lgkmcnt(0)
	v_mfma_f32_32x32x16_bf16 v[80:95], v[64:67], v[96:99], 0
	v_mfma_f32_32x32x16_bf16 v[64:79], v[68:71], v[96:99], 0
	v_mfma_f32_32x32x16_bf16 v[80:95], v[188:191], v[100:103], v[80:95]
	v_mfma_f32_32x32x16_bf16 v[64:79], v[192:195], v[100:103], v[64:79]
	v_mfma_f32_32x32x16_bf16 v[80:95], v[196:199], v[104:107], v[80:95]
	v_mfma_f32_32x32x16_bf16 v[64:79], v[200:203], v[104:107], v[64:79]
	v_mfma_f32_32x32x16_bf16 v[80:95], v[208:211], v[108:111], v[80:95]
	v_mfma_f32_32x32x16_bf16 v[64:79], v[214:217], v[108:111], v[64:79]
	s_setprio 0
	s_nop 10
	v_max_f32_e32 v147, v65, v65
	v_max_f32_e32 v149, v81, v81
	v_max_f32_e32 v147, v149, v147
	v_max_f32_e32 v149, v66, v66
	v_max_f32_e32 v151, v82, v82
	v_max_f32_e32 v149, v151, v149
	v_max_f32_e32 v151, v67, v67
	v_max_f32_e32 v187, v83, v83
	v_max3_f32 v147, v80, v64, v147
	v_max_f32_e32 v151, v187, v151
	v_max3_f32 v147, v147, v149, v151
	v_max_f32_e32 v149, v68, v68
	v_max_f32_e32 v151, v84, v84
	v_max_f32_e32 v149, v151, v149
	v_max_f32_e32 v151, v69, v69
	v_max_f32_e32 v187, v85, v85
	v_max_f32_e32 v151, v187, v151
	v_max3_f32 v147, v147, v149, v151
	v_max_f32_e32 v149, v70, v70
	v_max_f32_e32 v151, v86, v86
	v_max_f32_e32 v149, v151, v149
	v_max_f32_e32 v151, v71, v71
	v_max_f32_e32 v187, v87, v87
	v_max_f32_e32 v151, v187, v151
	v_max3_f32 v147, v147, v149, v151
	v_max_f32_e32 v149, v72, v72
	v_max_f32_e32 v151, v88, v88
	v_max_f32_e32 v149, v151, v149
	v_max_f32_e32 v151, v73, v73
	v_max_f32_e32 v187, v89, v89
	v_max_f32_e32 v151, v187, v151
	v_max3_f32 v147, v147, v149, v151
	v_max_f32_e32 v149, v74, v74
	v_max_f32_e32 v151, v90, v90
	v_max_f32_e32 v149, v151, v149
	v_max_f32_e32 v151, v75, v75
	v_max_f32_e32 v187, v91, v91
	v_max_f32_e32 v151, v187, v151
	v_max3_f32 v147, v147, v149, v151
	v_max_f32_e32 v149, v76, v76
	v_max_f32_e32 v151, v92, v92
	v_max_f32_e32 v149, v151, v149
	v_max_f32_e32 v151, v77, v77
	v_max_f32_e32 v187, v93, v93
	v_max_f32_e32 v151, v187, v151
	v_max3_f32 v147, v147, v149, v151
	v_max_f32_e32 v149, v78, v78
	v_max_f32_e32 v151, v94, v94
	v_max_f32_e32 v149, v151, v149
	v_max_f32_e32 v151, v79, v79
	v_max_f32_e32 v187, v95, v95
	v_max_f32_e32 v151, v187, v151
	v_max3_f32 v147, v147, v149, v151
	v_mov_b32_e32 v149, v147
	s_nop 1
	v_permlane32_swap_b32_e32 v147, v149
	v_max_f32_e32 v149, v149, v149
	v_max_f32_e32 v147, v147, v147
	v_max_f32_e32 v147, v147, v149
	v_cmp_gt_f32_e32 vcc, v147, v145
	s_cbranch_vccz .LBB0_235
	v_max_f32_e32 v147, v147, v147
	v_max_f32_e32 v149, v145, v145
	v_max_f32_e32 v147, v149, v147
	v_sub_f32_e32 v145, v145, v147
	v_exp_f32_e32 v188, v145
	v_mov_b32_e32 v145, v147
	v_pk_mul_f32 v[62:63], v[62:63], v[188:189] op_sel_hi:[1,0]
	v_pk_mul_f32 v[60:61], v[60:61], v[188:189] op_sel_hi:[1,0]
	v_pk_mul_f32 v[58:59], v[58:59], v[188:189] op_sel_hi:[1,0]
	v_pk_mul_f32 v[56:57], v[56:57], v[188:189] op_sel_hi:[1,0]
	v_pk_mul_f32 v[54:55], v[54:55], v[188:189] op_sel_hi:[1,0]
	v_pk_mul_f32 v[52:53], v[52:53], v[188:189] op_sel_hi:[1,0]
	v_pk_mul_f32 v[50:51], v[50:51], v[188:189] op_sel_hi:[1,0]
	v_pk_mul_f32 v[48:49], v[48:49], v[188:189] op_sel_hi:[1,0]
	v_pk_mul_f32 v[46:47], v[46:47], v[188:189] op_sel_hi:[1,0]
	v_pk_mul_f32 v[44:45], v[44:45], v[188:189] op_sel_hi:[1,0]
	v_pk_mul_f32 v[42:43], v[42:43], v[188:189] op_sel_hi:[1,0]
	v_pk_mul_f32 v[40:41], v[40:41], v[188:189] op_sel_hi:[1,0]
	v_pk_mul_f32 v[38:39], v[38:39], v[188:189] op_sel_hi:[1,0]
	v_pk_mul_f32 v[36:37], v[36:37], v[188:189] op_sel_hi:[1,0]
	v_pk_mul_f32 v[34:35], v[34:35], v[188:189] op_sel_hi:[1,0]
	v_pk_mul_f32 v[32:33], v[32:33], v[188:189] op_sel_hi:[1,0]
	v_pk_mul_f32 v[30:31], v[30:31], v[188:189] op_sel_hi:[1,0]
	v_pk_mul_f32 v[28:29], v[28:29], v[188:189] op_sel_hi:[1,0]
	v_pk_mul_f32 v[26:27], v[26:27], v[188:189] op_sel_hi:[1,0]
	v_pk_mul_f32 v[24:25], v[24:25], v[188:189] op_sel_hi:[1,0]
	v_pk_mul_f32 v[22:23], v[22:23], v[188:189] op_sel_hi:[1,0]
	v_pk_mul_f32 v[20:21], v[20:21], v[188:189] op_sel_hi:[1,0]
	v_pk_mul_f32 v[18:19], v[18:19], v[188:189] op_sel_hi:[1,0]
	v_pk_mul_f32 v[16:17], v[16:17], v[188:189] op_sel_hi:[1,0]
	v_pk_mul_f32 v[14:15], v[14:15], v[188:189] op_sel_hi:[1,0]
	v_pk_mul_f32 v[12:13], v[12:13], v[188:189] op_sel_hi:[1,0]
	v_pk_mul_f32 v[10:11], v[10:11], v[188:189] op_sel_hi:[1,0]
	v_pk_mul_f32 v[8:9], v[8:9], v[188:189] op_sel_hi:[1,0]
	v_pk_mul_f32 v[6:7], v[6:7], v[188:189] op_sel_hi:[1,0]
	v_pk_mul_f32 v[4:5], v[4:5], v[188:189] op_sel_hi:[1,0]
	v_pk_mul_f32 v[2:3], v[2:3], v[188:189] op_sel_hi:[1,0]
	v_pk_mul_f32 v[0:1], v[0:1], v[188:189] op_sel_hi:[1,0]
	v_mul_f32_e32 v143, v143, v188
	s_branch .LBB0_235

; #define PG8_STAGE(bufoff, gbase, voff) do { _Pragma("unroll") for (int _i = 0; _i < 2; ++_i) \
;         __builtin_amdgcn_global_load_lds((const unsigned*)((const char*)(gbase) + (voff)[_i]), (LAS unsigned*)(lds + (bufoff) + ldsw + _i * 8192), 16, 0, 0); } while (0)
; #define PG8_LDA(dst, b, h) do { _Pragma("unroll") for (int m = 0; m < 4; ++m) _Pragma("unroll") for (int k = 0; k < 2; ++k) dst[m][k] = *(const LAS bf16x8*)(lds + PG8_SA(b, h) + aoff + m * 2048 + k * 1024); } while (0)
; #define PG8_LDB(dst, b, h) do { _Pragma("unroll") for (int n = 0; n < 2; ++n) _Pragma("unroll") for (int k = 0; k < 2; ++k) dst[n][k] = *(const LAS bf16x8*)(lds + PG8_SB(b, h) + boff + n * 2048 + k * 1024); } while (0)
; #define PG8_MMA(ai, bj, At, Bt) do { __builtin_amdgcn_s_setprio(1); _Pragma("unroll") for (int m = 0; m < 4; ++m) _Pragma("unroll") for (int n = 0; n < 2; ++n) _Pragma("unroll") for (int k = 0; k < 2; ++k) \
;         acc[ai][bj][m][n] = __builtin_amdgcn_mfma_f32_16x16x32_bf16(Bt[n][k], At[m][k], acc[ai][bj][m][n], 0, 0, 0); __builtin_amdgcn_s_setprio(0); } while (0)
; #define PG8_WAIT_V(n) asm volatile("s_waitcnt vmcnt(" #n ")" ::: "memory")
; #define PG8_WAIT_L(n) asm volatile("s_waitcnt lgkmcnt(" #n ")" ::: "memory")
; #define PG8_BAR __builtin_amdgcn_s_barrier()
; #define PG8_SCHED __builtin_amdgcn_sched_barrier(0)
;     ...
;             PG8_LDB(B0, 0, 0); PG8_LDB(B1, 0, 1); PG8_SCHED; PG8_LDA(At, 0, 0); PG8_STAGE(PG8_SA(1, 1), a1 + hA, voffA);
;             PG8_WAIT_V(8); PG8_WAIT_L(0); PG8_BAR; PG8_MMA(0, 0, At, B0); PG8_MMA(0, 1, At, B1); PG8_BAR; PG8_SCHED;
;             PG8_LDA(At, 0, 1); PG8_STAGE(PG8_SB(0, 0), b2, voffB); PG8_STAGE(PG8_SB(0, 1), b2 + hB, voffB); PG8_STAGE(PG8_SA(0, 0), a2, voffA);
;             PG8_WAIT_V(8); PG8_WAIT_L(0); PG8_BAR; PG8_MMA(1, 0, At, B0); PG8_MMA(1, 1, At, B1); PG8_BAR; PG8_SCHED;
.LBB0_299:
	s_add_u32 s72, s44, s52
	s_addc_u32 s73, s45, s53
	s_add_u32 s76, s72, 0x100
	s_addc_u32 s77, s73, 0
	s_add_u32 s74, s79, s52
	s_addc_u32 s75, s80, s53
	s_add_u32 s72, s72, 0x180
	s_addc_u32 s73, s73, 0
	s_add_i32 s82, 0, 0x10000
	s_add_i32 s89, 0, 0x14000
	v_add_u32_e32 v144, s82, v193
	v_add_u32_e32 v184, s89, v193
	ds_read_b128 v[132:135], v144
	ds_read_b128 v[136:139], v144 offset:1024
	ds_read_b128 v[140:143], v144 offset:2048
	ds_read_b128 v[144:147], v144 offset:3072
	ds_read_b128 v[148:151], v184
	ds_read_b128 v[176:179], v184 offset:1024
	ds_read_b128 v[180:183], v184 offset:2048
	ds_read_b128 v[184:187], v184 offset:3072
	s_cmpk_eq_i32 s52, 0x700
	s_cselect_b32 s73, s78, s73
	s_cselect_b32 s72, s55, s72
	s_cselect_b32 s75, s27, s75
	s_cselect_b32 s74, s54, s74
	s_cselect_b32 s77, s3, s77
	s_cselect_b32 s76, s29, s76
	v_lshl_add_u64 v[196:197], v[128:129], 0, s[52:53]
	s_add_i32 m0, s6, 0xc000
	ds_read_b128 v[188:191], v198
	ds_read_b128 v[200:203], v198 offset:1024
	ds_read_b128 v[208:211], v198 offset:2048
	ds_read_b128 v[214:217], v198 offset:3072
	ds_read_b128 v[230:233], v198 offset:4096
	ds_read_b128 v[234:237], v198 offset:5120
	ds_read_b128 v[238:241], v198 offset:6144
	ds_read_b128 v[242:245], v198 offset:7168
	global_load_lds_dwordx4 v[196:197], off
	v_lshl_add_u64 v[196:197], v[130:131], 0, s[52:53]
	s_add_i32 m0, s6, 0xe000
	s_nop 0
	global_load_lds_dwordx4 v[196:197], off
	s_waitcnt vmcnt(8)
	s_waitcnt lgkmcnt(0)
	s_barrier
	s_setprio 1
	s_waitcnt lgkmcnt(0)
	v_mfma_f32_16x16x32_bf16 v[124:127], v[132:135], v[188:191], v[124:127]
	v_mfma_f32_16x16x32_bf16 v[120:123], v[140:143], v[188:191], v[120:123]
	v_mfma_f32_16x16x32_bf16 v[108:111], v[132:135], v[208:211], v[108:111]
	v_mfma_f32_16x16x32_bf16 v[104:107], v[140:143], v[208:211], v[104:107]
	v_mfma_f32_16x16x32_bf16 v[92:95], v[132:135], v[230:233], v[92:95]
	v_mfma_f32_16x16x32_bf16 v[88:91], v[140:143], v[230:233], v[88:91]
	v_mfma_f32_16x16x32_bf16 v[76:79], v[132:135], v[238:241], v[76:79]
	v_mfma_f32_16x16x32_bf16 v[72:75], v[140:143], v[238:241], v[72:75]
	v_mfma_f32_16x16x32_bf16 v[124:127], v[136:139], v[200:203], v[124:127]
	v_mfma_f32_16x16x32_bf16 v[120:123], v[144:147], v[200:203], v[120:123]
	v_mfma_f32_16x16x32_bf16 v[108:111], v[136:139], v[214:217], v[108:111]
	v_mfma_f32_16x16x32_bf16 v[104:107], v[144:147], v[214:217], v[104:107]
	v_mfma_f32_16x16x32_bf16 v[92:95], v[136:139], v[234:237], v[92:95]
	v_mfma_f32_16x16x32_bf16 v[88:91], v[144:147], v[234:237], v[88:91]
	v_mfma_f32_16x16x32_bf16 v[76:79], v[136:139], v[242:245], v[76:79]
	v_mfma_f32_16x16x32_bf16 v[72:75], v[144:147], v[242:245], v[72:75]
	s_setprio 0
	s_setprio 1
	v_mfma_f32_16x16x32_bf16 v[116:119], v[148:151], v[188:191], v[116:119]
	v_mfma_f32_16x16x32_bf16 v[112:115], v[180:183], v[188:191], v[112:115]
	v_mfma_f32_16x16x32_bf16 v[100:103], v[148:151], v[208:211], v[100:103]
	v_mfma_f32_16x16x32_bf16 v[96:99], v[180:183], v[208:211], v[96:99]
	v_mfma_f32_16x16x32_bf16 v[84:87], v[148:151], v[230:233], v[84:87]
	v_mfma_f32_16x16x32_bf16 v[80:83], v[180:183], v[230:233], v[80:83]
	v_mfma_f32_16x16x32_bf16 v[68:71], v[148:151], v[238:241], v[68:71]
	v_mfma_f32_16x16x32_bf16 v[64:67], v[180:183], v[238:241], v[64:67]
	v_mfma_f32_16x16x32_bf16 v[116:119], v[176:179], v[200:203], v[116:119]
	v_mfma_f32_16x16x32_bf16 v[112:115], v[184:187], v[200:203], v[112:115]
	v_mfma_f32_16x16x32_bf16 v[100:103], v[176:179], v[214:217], v[100:103]
	v_mfma_f32_16x16x32_bf16 v[96:99], v[184:187], v[214:217], v[96:99]
	v_mfma_f32_16x16x32_bf16 v[84:87], v[176:179], v[234:237], v[84:87]
	v_mfma_f32_16x16x32_bf16 v[80:83], v[184:187], v[234:237], v[80:83]
	v_mfma_f32_16x16x32_bf16 v[68:71], v[176:179], v[242:245], v[68:71]
	v_mfma_f32_16x16x32_bf16 v[64:67], v[184:187], v[242:245], v[64:67]
	s_setprio 0
	s_barrier
	s_add_i32 s82, s82, s5
	v_lshl_add_u64 v[196:197], s[74:75], 0, v[156:157]
	s_mov_b32 m0, s82
	ds_read_b128 v[188:191], v198 offset:16384
	ds_read_b128 v[200:203], v198 offset:17408
	ds_read_b128 v[208:211], v198 offset:18432
	ds_read_b128 v[214:217], v198 offset:19456
	ds_read_b128 v[230:233], v198 offset:20480
	ds_read_b128 v[234:237], v198 offset:21504
	ds_read_b128 v[238:241], v198 offset:22528
	ds_read_b128 v[242:245], v198 offset:23552
	global_load_lds_dwordx4 v[196:197], off
	s_add_i32 m0, s82, 0x2000
	s_add_u32 s82, s74, 0x40000
	v_lshl_add_u64 v[204:205], s[74:75], 0, v[168:169]
	s_addc_u32 s83, s75, 0
	s_add_i32 s89, s89, s5
	global_load_lds_dwordx4 v[204:205], off
	v_lshl_add_u64 v[206:207], s[82:83], 0, v[156:157]
	s_mov_b32 m0, s89
	s_nop 0
	global_load_lds_dwordx4 v[206:207], off
	v_lshl_add_u64 v[206:207], s[82:83], 0, v[168:169]
	s_add_i32 m0, s89, 0x2000
	s_nop 0
	global_load_lds_dwordx4 v[206:207], off
	v_lshl_add_u64 v[206:207], s[76:77], 0, v[152:153]
	s_mov_b32 m0, s6
	s_nop 0
	global_load_lds_dwordx4 v[206:207], off
	v_lshl_add_u64 v[206:207], s[76:77], 0, v[154:155]
	s_mov_b32 m0, s7
	s_nop 0
	global_load_lds_dwordx4 v[206:207], off
	s_waitcnt vmcnt(8)
	s_waitcnt lgkmcnt(0)
	s_barrier
; #define PG8_STAGE(bufoff, gbase, voff) do { _Pragma("unroll") for (int _i = 0; _i < 2; ++_i) \
;         __builtin_amdgcn_global_load_lds((const unsigned*)((const char*)(gbase) + (voff)[_i]), (LAS unsigned*)(lds + (bufoff) + ldsw + _i * 8192), 16, 0, 0); } while (0)
; #define PG8_LDA(dst, b, h) do { _Pragma("unroll") for (int m = 0; m < 4; ++m) _Pragma("unroll") for (int k = 0; k < 2; ++k) dst[m][k] = *(const LAS bf16x8*)(lds + PG8_SA(b, h) + aoff + m * 2048 + k * 1024); } while (0)
; #define PG8_LDB(dst, b, h) do { _Pragma("unroll") for (int n = 0; n < 2; ++n) _Pragma("unroll") for (int k = 0; k < 2; ++k) dst[n][k] = *(const LAS bf16x8*)(lds + PG8_SB(b, h) + boff + n * 2048 + k * 1024); } while (0)
; #define PG8_MMA(ai, bj, At, Bt) do { __builtin_amdgcn_s_setprio(1); _Pragma("unroll") for (int m = 0; m < 4; ++m) _Pragma("unroll") for (int n = 0; n < 2; ++n) _Pragma("unroll") for (int k = 0; k < 2; ++k) \
;         acc[ai][bj][m][n] = __builtin_amdgcn_mfma_f32_16x16x32_bf16(Bt[n][k], At[m][k], acc[ai][bj][m][n], 0, 0, 0); __builtin_amdgcn_s_setprio(0); } while (0)
; #define PG8_WAIT_V(n) asm volatile("s_waitcnt vmcnt(" #n ")" ::: "memory")
; #define PG8_WAIT_L(n) asm volatile("s_waitcnt lgkmcnt(" #n ")" ::: "memory")
; #define PG8_BAR __builtin_amdgcn_s_barrier()
; #define PG8_SCHED __builtin_amdgcn_sched_barrier(0)
;     ...
;             PG8_LDB(B0, 1, 0); PG8_LDB(B1, 1, 1); PG8_SCHED; PG8_LDA(At, 1, 0); PG8_STAGE(PG8_SA(0, 1), a2 + hA, voffA);
;             PG8_WAIT_V(8); PG8_WAIT_L(0); PG8_BAR; PG8_MMA(0, 0, At, B0); PG8_MMA(0, 1, At, B1); PG8_BAR; PG8_SCHED;
;             PG8_LDA(At, 1, 1); PG8_STAGE(PG8_SB(1, 0), b3, voffB); PG8_STAGE(PG8_SB(1, 1), b3 + hB, voffB); PG8_STAGE(PG8_SA(1, 0), a3, voffA);
	s_setprio 1
	s_waitcnt lgkmcnt(0)
	v_mfma_f32_16x16x32_bf16 v[60:63], v[132:135], v[188:191], v[60:63]
	v_mfma_f32_16x16x32_bf16 v[56:59], v[140:143], v[188:191], v[56:59]
	v_mfma_f32_16x16x32_bf16 v[44:47], v[132:135], v[208:211], v[44:47]
	v_mfma_f32_16x16x32_bf16 v[40:43], v[140:143], v[208:211], v[40:43]
	v_mfma_f32_16x16x32_bf16 v[28:31], v[132:135], v[230:233], v[28:31]
	v_mfma_f32_16x16x32_bf16 v[24:27], v[140:143], v[230:233], v[24:27]
	v_mfma_f32_16x16x32_bf16 v[12:15], v[132:135], v[238:241], v[12:15]
	v_mfma_f32_16x16x32_bf16 v[8:11], v[140:143], v[238:241], v[8:11]
	v_mfma_f32_16x16x32_bf16 v[60:63], v[136:139], v[200:203], v[60:63]
	v_mfma_f32_16x16x32_bf16 v[56:59], v[144:147], v[200:203], v[56:59]
	v_mfma_f32_16x16x32_bf16 v[44:47], v[136:139], v[214:217], v[44:47]
	v_mfma_f32_16x16x32_bf16 v[40:43], v[144:147], v[214:217], v[40:43]
	v_mfma_f32_16x16x32_bf16 v[28:31], v[136:139], v[234:237], v[28:31]
	v_mfma_f32_16x16x32_bf16 v[24:27], v[144:147], v[234:237], v[24:27]
	v_mfma_f32_16x16x32_bf16 v[12:15], v[136:139], v[242:245], v[12:15]
	v_mfma_f32_16x16x32_bf16 v[8:11], v[144:147], v[242:245], v[8:11]
	s_setprio 0
	s_setprio 1
	v_mfma_f32_16x16x32_bf16 v[52:55], v[148:151], v[188:191], v[52:55]
	v_mfma_f32_16x16x32_bf16 v[48:51], v[180:183], v[188:191], v[48:51]
	v_mfma_f32_16x16x32_bf16 v[36:39], v[148:151], v[208:211], v[36:39]
	v_mfma_f32_16x16x32_bf16 v[32:35], v[180:183], v[208:211], v[32:35]
	v_mfma_f32_16x16x32_bf16 v[20:23], v[148:151], v[230:233], v[20:23]
	v_mfma_f32_16x16x32_bf16 v[16:19], v[180:183], v[230:233], v[16:19]
	v_mfma_f32_16x16x32_bf16 v[4:7], v[148:151], v[238:241], v[4:7]
	v_mfma_f32_16x16x32_bf16 v[0:3], v[180:183], v[238:241], v[0:3]
	v_mfma_f32_16x16x32_bf16 v[52:55], v[176:179], v[200:203], v[52:55]
	v_mfma_f32_16x16x32_bf16 v[48:51], v[184:187], v[200:203], v[48:51]
	v_mfma_f32_16x16x32_bf16 v[36:39], v[176:179], v[214:217], v[36:39]
	v_mfma_f32_16x16x32_bf16 v[32:35], v[184:187], v[214:217], v[32:35]
	v_mfma_f32_16x16x32_bf16 v[20:23], v[176:179], v[234:237], v[20:23]
	v_mfma_f32_16x16x32_bf16 v[16:19], v[184:187], v[234:237], v[16:19]
	v_mfma_f32_16x16x32_bf16 v[4:7], v[176:179], v[242:245], v[4:7]
	v_mfma_f32_16x16x32_bf16 v[0:3], v[184:187], v[242:245], v[0:3]
	s_setprio 0
	s_barrier
	s_add_i32 s82, 0, 0x18000
	s_add_i32 s83, 0, 0x1c000
	v_add_u32_e32 v144, s82, v193
	v_add_u32_e32 v184, s83, v193
	ds_read_b128 v[132:135], v144
	ds_read_b128 v[136:139], v144 offset:1024
	ds_read_b128 v[140:143], v144 offset:2048
	ds_read_b128 v[144:147], v144 offset:3072
	ds_read_b128 v[148:151], v184
	ds_read_b128 v[176:179], v184 offset:1024
	ds_read_b128 v[180:183], v184 offset:2048
	ds_read_b128 v[184:187], v184 offset:3072
	s_add_u32 s76, s76, 0x40000
	s_addc_u32 s77, s77, 0
	s_mov_b32 m0, s8
	v_lshl_add_u64 v[206:207], s[76:77], 0, v[152:153]
	ds_read_b128 v[188:191], v198 offset:32768
	ds_read_b128 v[200:203], v198 offset:33792
	ds_read_b128 v[208:211], v198 offset:34816
	ds_read_b128 v[214:217], v198 offset:35840
	ds_read_b128 v[230:233], v198 offset:36864
	ds_read_b128 v[234:237], v198 offset:37888
	ds_read_b128 v[238:241], v198 offset:38912
	ds_read_b128 v[242:245], v198 offset:39936
	global_load_lds_dwordx4 v[206:207], off
	v_lshl_add_u64 v[206:207], s[76:77], 0, v[154:155]
	s_mov_b32 m0, s9
	s_nop 0
	global_load_lds_dwordx4 v[206:207], off
	s_waitcnt vmcnt(8)
	s_waitcnt lgkmcnt(0)
	s_barrier
	s_setprio 1
	s_waitcnt lgkmcnt(0)
	v_mfma_f32_16x16x32_bf16 v[124:127], v[132:135], v[188:191], v[124:127]
	v_mfma_f32_16x16x32_bf16 v[120:123], v[140:143], v[188:191], v[120:123]
	v_mfma_f32_16x16x32_bf16 v[108:111], v[132:135], v[208:211], v[108:111]
	v_mfma_f32_16x16x32_bf16 v[104:107], v[140:143], v[208:211], v[104:107]
	v_mfma_f32_16x16x32_bf16 v[92:95], v[132:135], v[230:233], v[92:95]
	v_mfma_f32_16x16x32_bf16 v[88:91], v[140:143], v[230:233], v[88:91]
	v_mfma_f32_16x16x32_bf16 v[76:79], v[132:135], v[238:241], v[76:79]
	v_mfma_f32_16x16x32_bf16 v[72:75], v[140:143], v[238:241], v[72:75]
	v_mfma_f32_16x16x32_bf16 v[124:127], v[136:139], v[200:203], v[124:127]
	v_mfma_f32_16x16x32_bf16 v[120:123], v[144:147], v[200:203], v[120:123]
	v_mfma_f32_16x16x32_bf16 v[108:111], v[136:139], v[214:217], v[108:111]
	v_mfma_f32_16x16x32_bf16 v[104:107], v[144:147], v[214:217], v[104:107]
	v_mfma_f32_16x16x32_bf16 v[92:95], v[136:139], v[234:237], v[92:95]
	v_mfma_f32_16x16x32_bf16 v[88:91], v[144:147], v[234:237], v[88:91]
	v_mfma_f32_16x16x32_bf16 v[76:79], v[136:139], v[242:245], v[76:79]
	v_mfma_f32_16x16x32_bf16 v[72:75], v[144:147], v[242:245], v[72:75]
	s_setprio 0
	s_setprio 1
	v_mfma_f32_16x16x32_bf16 v[116:119], v[148:151], v[188:191], v[116:119]
	v_mfma_f32_16x16x32_bf16 v[112:115], v[180:183], v[188:191], v[112:115]
	v_mfma_f32_16x16x32_bf16 v[100:103], v[148:151], v[208:211], v[100:103]
	v_mfma_f32_16x16x32_bf16 v[96:99], v[180:183], v[208:211], v[96:99]
	v_mfma_f32_16x16x32_bf16 v[84:87], v[148:151], v[230:233], v[84:87]
	v_mfma_f32_16x16x32_bf16 v[80:83], v[180:183], v[230:233], v[80:83]
	v_mfma_f32_16x16x32_bf16 v[68:71], v[148:151], v[238:241], v[68:71]
	v_mfma_f32_16x16x32_bf16 v[64:67], v[180:183], v[238:241], v[64:67]
	v_mfma_f32_16x16x32_bf16 v[116:119], v[176:179], v[200:203], v[116:119]
	v_mfma_f32_16x16x32_bf16 v[112:115], v[184:187], v[200:203], v[112:115]
	v_mfma_f32_16x16x32_bf16 v[100:103], v[176:179], v[214:217], v[100:103]
	v_mfma_f32_16x16x32_bf16 v[96:99], v[184:187], v[214:217], v[96:99]
	v_mfma_f32_16x16x32_bf16 v[84:87], v[176:179], v[234:237], v[84:87]
	v_mfma_f32_16x16x32_bf16 v[80:83], v[184:187], v[234:237], v[80:83]
	v_mfma_f32_16x16x32_bf16 v[68:71], v[176:179], v[242:245], v[68:71]
	v_mfma_f32_16x16x32_bf16 v[64:67], v[184:187], v[242:245], v[64:67]
	s_setprio 0
	s_barrier
; #define PG8_STAGE(bufoff, gbase, voff) do { _Pragma("unroll") for (int _i = 0; _i < 2; ++_i) \
;         __builtin_amdgcn_global_load_lds((const unsigned*)((const char*)(gbase) + (voff)[_i]), (LAS unsigned*)(lds + (bufoff) + ldsw + _i * 8192), 16, 0, 0); } while (0)
; #define PG8_LDA(dst, b, h) do { _Pragma("unroll") for (int m = 0; m < 4; ++m) _Pragma("unroll") for (int k = 0; k < 2; ++k) dst[m][k] = *(const LAS bf16x8*)(lds + PG8_SA(b, h) + aoff + m * 2048 + k * 1024); } while (0)
; #define PG8_MMA(ai, bj, At, Bt) do { __builtin_amdgcn_s_setprio(1); _Pragma("unroll") for (int m = 0; m < 4; ++m) _Pragma("unroll") for (int n = 0; n < 2; ++n) _Pragma("unroll") for (int k = 0; k < 2; ++k) \
;         acc[ai][bj][m][n] = __builtin_amdgcn_mfma_f32_16x16x32_bf16(Bt[n][k], At[m][k], acc[ai][bj][m][n], 0, 0, 0); __builtin_amdgcn_s_setprio(0); } while (0)
; #define PG8_WAIT_V(n) asm volatile("s_waitcnt vmcnt(" #n ")" ::: "memory")
; #define PG8_WAIT_L(n) asm volatile("s_waitcnt lgkmcnt(" #n ")" ::: "memory")
; #define PG8_BAR __builtin_amdgcn_s_barrier()
; #define PG8_SCHED __builtin_amdgcn_sched_barrier(0)
;     ...
;             PG8_LDA(At, 1, 1); PG8_STAGE(PG8_SB(1, 0), b3, voffB); PG8_STAGE(PG8_SB(1, 1), b3 + hB, voffB); PG8_STAGE(PG8_SA(1, 0), a3, voffA);
;             PG8_WAIT_V(8); PG8_WAIT_L(0); PG8_BAR; PG8_MMA(1, 0, At, B0); PG8_MMA(1, 1, At, B1); PG8_BAR; PG8_SCHED;
	s_add_i32 s76, s82, s5
	v_lshl_add_u64 v[196:197], v[196:197], 0, s[38:39]
	s_mov_b32 m0, s76
	ds_read_b128 v[188:191], v198 offset:49152
	ds_read_b128 v[200:203], v198 offset:50176
	ds_read_b128 v[208:211], v198 offset:51200
	ds_read_b128 v[214:217], v198 offset:52224
	ds_read_b128 v[230:233], v198 offset:53248
	ds_read_b128 v[234:237], v198 offset:54272
	ds_read_b128 v[238:241], v198 offset:55296
	ds_read_b128 v[242:245], v198 offset:56320
	global_load_lds_dwordx4 v[196:197], off
	s_add_i32 m0, s76, 0x2000
	s_add_u32 s74, s74, 0x40080
	v_lshl_add_u64 v[196:197], v[204:205], 0, s[38:39]
	s_addc_u32 s75, s75, 0
	s_add_i32 s76, s83, s5
	global_load_lds_dwordx4 v[196:197], off
	v_lshl_add_u64 v[196:197], s[74:75], 0, v[156:157]
	s_mov_b32 m0, s76
	s_nop 0
	global_load_lds_dwordx4 v[196:197], off
	v_lshl_add_u64 v[196:197], s[74:75], 0, v[168:169]
	s_add_i32 m0, s76, 0x2000
	s_nop 0
	global_load_lds_dwordx4 v[196:197], off
	v_lshl_add_u64 v[196:197], s[72:73], 0, v[152:153]
	s_mov_b32 m0, s36
	s_nop 0
	global_load_lds_dwordx4 v[196:197], off
	v_lshl_add_u64 v[196:197], s[72:73], 0, v[154:155]
	s_mov_b32 m0, s42
	s_nop 0
	global_load_lds_dwordx4 v[196:197], off
	s_waitcnt vmcnt(8)
	s_waitcnt lgkmcnt(0)
	s_barrier
	s_setprio 1
	s_waitcnt lgkmcnt(0)
	v_mfma_f32_16x16x32_bf16 v[60:63], v[132:135], v[188:191], v[60:63]
	v_mfma_f32_16x16x32_bf16 v[56:59], v[140:143], v[188:191], v[56:59]
	v_mfma_f32_16x16x32_bf16 v[44:47], v[132:135], v[208:211], v[44:47]
	v_mfma_f32_16x16x32_bf16 v[40:43], v[140:143], v[208:211], v[40:43]
	v_mfma_f32_16x16x32_bf16 v[28:31], v[132:135], v[230:233], v[28:31]
	v_mfma_f32_16x16x32_bf16 v[24:27], v[140:143], v[230:233], v[24:27]
	v_mfma_f32_16x16x32_bf16 v[12:15], v[132:135], v[238:241], v[12:15]
	v_mfma_f32_16x16x32_bf16 v[8:11], v[140:143], v[238:241], v[8:11]
	v_mfma_f32_16x16x32_bf16 v[60:63], v[136:139], v[200:203], v[60:63]
	v_mfma_f32_16x16x32_bf16 v[56:59], v[144:147], v[200:203], v[56:59]
	v_mfma_f32_16x16x32_bf16 v[44:47], v[136:139], v[214:217], v[44:47]
	v_mfma_f32_16x16x32_bf16 v[40:43], v[144:147], v[214:217], v[40:43]
	v_mfma_f32_16x16x32_bf16 v[28:31], v[136:139], v[234:237], v[28:31]
	v_mfma_f32_16x16x32_bf16 v[24:27], v[144:147], v[234:237], v[24:27]
	v_mfma_f32_16x16x32_bf16 v[12:15], v[136:139], v[242:245], v[12:15]
	v_mfma_f32_16x16x32_bf16 v[8:11], v[144:147], v[242:245], v[8:11]
	s_setprio 0
	s_setprio 1
	v_mfma_f32_16x16x32_bf16 v[52:55], v[148:151], v[188:191], v[52:55]
	v_mfma_f32_16x16x32_bf16 v[48:51], v[180:183], v[188:191], v[48:51]
	v_mfma_f32_16x16x32_bf16 v[36:39], v[148:151], v[208:211], v[36:39]
	v_mfma_f32_16x16x32_bf16 v[32:35], v[180:183], v[208:211], v[32:35]
	v_mfma_f32_16x16x32_bf16 v[20:23], v[148:151], v[230:233], v[20:23]
	v_mfma_f32_16x16x32_bf16 v[16:19], v[180:183], v[230:233], v[16:19]
	v_mfma_f32_16x16x32_bf16 v[4:7], v[148:151], v[238:241], v[4:7]
	v_mfma_f32_16x16x32_bf16 v[0:3], v[180:183], v[238:241], v[0:3]
	v_mfma_f32_16x16x32_bf16 v[52:55], v[176:179], v[200:203], v[52:55]
	v_mfma_f32_16x16x32_bf16 v[48:51], v[184:187], v[200:203], v[48:51]
	v_mfma_f32_16x16x32_bf16 v[36:39], v[176:179], v[214:217], v[36:39]
	v_mfma_f32_16x16x32_bf16 v[32:35], v[184:187], v[214:217], v[32:35]
	v_mfma_f32_16x16x32_bf16 v[20:23], v[176:179], v[234:237], v[20:23]
	v_mfma_f32_16x16x32_bf16 v[16:19], v[184:187], v[234:237], v[16:19]
	v_mfma_f32_16x16x32_bf16 v[4:7], v[176:179], v[242:245], v[4:7]
	v_mfma_f32_16x16x32_bf16 v[0:3], v[184:187], v[242:245], v[0:3]
	s_setprio 0
	s_barrier
	s_add_i32 s81, s81, 2
	s_add_u32 s52, s52, 0x100
	s_addc_u32 s53, s53, 0
	s_cmp_gt_u32 s81, 13
	s_cbranch_scc0 .LBB0_299
	s_and_b64 vcc, exec, s[16:17]
	s_cbranch_vccz .LBB0_302
	s_barrier

; #define PG8_STAGE(bufoff, gbase, voff) do { _Pragma("unroll") for (int _i = 0; _i < 2; ++_i) \
;         __builtin_amdgcn_global_load_lds((const unsigned*)((const char*)(gbase) + (voff)[_i]), (LAS unsigned*)(lds + (bufoff) + ldsw + _i * 8192), 16, 0, 0); } while (0)
; #define PG8_LDA(dst, b, h) do { _Pragma("unroll") for (int m = 0; m < 4; ++m) _Pragma("unroll") for (int k = 0; k < 2; ++k) dst[m][k] = *(const LAS bf16x8*)(lds + PG8_SA(b, h) + aoff + m * 2048 + k * 1024); } while (0)
; #define PG8_LDB(dst, b, h) do { _Pragma("unroll") for (int n = 0; n < 2; ++n) _Pragma("unroll") for (int k = 0; k < 2; ++k) dst[n][k] = *(const LAS bf16x8*)(lds + PG8_SB(b, h) + boff + n * 2048 + k * 1024); } while (0)
; #define PG8_MMA(ai, bj, At, Bt) do { __builtin_amdgcn_s_setprio(1); _Pragma("unroll") for (int m = 0; m < 4; ++m) _Pragma("unroll") for (int n = 0; n < 2; ++n) _Pragma("unroll") for (int k = 0; k < 2; ++k) \
;         acc[ai][bj][m][n] = __builtin_amdgcn_mfma_f32_16x16x32_bf16(Bt[n][k], At[m][k], acc[ai][bj][m][n], 0, 0, 0); __builtin_amdgcn_s_setprio(0); } while (0)
; #define PG8_WAIT_V(n) asm volatile("s_waitcnt vmcnt(" #n ")" ::: "memory")
; #define PG8_WAIT_L(n) asm volatile("s_waitcnt lgkmcnt(" #n ")" ::: "memory")
; #define PG8_BAR __builtin_amdgcn_s_barrier()
; #define PG8_SCHED __builtin_amdgcn_sched_barrier(0)
;     ...
;             PG8_LDB(B0, 0, 0); PG8_LDB(B1, 0, 1); PG8_SCHED; PG8_LDA(At, 0, 0); PG8_STAGE(PG8_SA(1, 1), a1 + hA, voffA);
;             PG8_WAIT_V(8); PG8_WAIT_L(0); PG8_BAR; PG8_MMA(0, 0, At, B0); PG8_MMA(0, 1, At, B1); PG8_BAR; PG8_SCHED;
;             PG8_LDA(At, 0, 1); PG8_STAGE(PG8_SB(0, 0), b2, voffB); PG8_STAGE(PG8_SB(0, 1), b2 + hB, voffB); PG8_STAGE(PG8_SA(0, 0), a2, voffA);
;             PG8_WAIT_V(8); PG8_WAIT_L(0); PG8_BAR; PG8_MMA(1, 0, At, B0); PG8_MMA(1, 1, At, B1); PG8_BAR; PG8_SCHED;
.LBB0_364:
	s_add_i32 s6, s74, 2
	s_add_u32 s26, s92, vcc_lo
	s_addc_u32 s27, s93, vcc_hi
	s_add_u32 s76, s26, 0x100
	s_addc_u32 s77, s27, 0
	s_add_u32 s9, s94, vcc_lo
	s_addc_u32 s8, s95, vcc_hi
	s_add_u32 s26, s26, 0x180
	s_addc_u32 s27, s27, 0
	s_add_i32 s50, 0, 0x10000
	s_add_i32 s51, 0, 0x14000
	v_add_u32_e32 v154, s50, v168
	ds_read_b128 v[132:135], v154
	ds_read_b128 v[146:149], v154 offset:1024
	ds_read_b128 v[150:153], v154 offset:2048
	ds_read_b128 v[172:175], v154 offset:3072
	v_add_u32_e32 v154, s51, v168
	ds_read_b128 v[176:179], v154
	ds_read_b128 v[180:183], v154 offset:1024
	ds_read_b128 v[184:187], v154 offset:2048
	ds_read_b128 v[188:191], v154 offset:3072
	s_cmp_eq_u32 s5, s74
	s_cselect_b32 s74, s97, s26
	s_cselect_b32 s75, s79, s27
	s_cselect_b32 s27, s45, s8
	s_cselect_b32 s26, s96, s9
	s_cselect_b32 s77, s43, s77
	s_cselect_b32 s76, s82, s76
	v_lshl_add_u64 v[154:155], v[130:131], 0, vcc
	s_add_i32 m0, s83, 0xc000
	ds_read_b128 v[192:195], v170
	ds_read_b128 v[196:199], v170 offset:1024
	ds_read_b128 v[200:203], v170 offset:2048
	ds_read_b128 v[208:211], v170 offset:3072
	ds_read_b128 v[214:217], v170 offset:4096
	ds_read_b128 v[230:233], v170 offset:5120
	ds_read_b128 v[234:237], v170 offset:6144
	ds_read_b128 v[238:241], v170 offset:7168
	global_load_lds_dwordx4 v[154:155], off
	v_lshl_add_u64 v[154:155], v[128:129], 0, vcc
	s_add_i32 m0, s83, 0xe000
	s_nop 0
	global_load_lds_dwordx4 v[154:155], off
	s_waitcnt vmcnt(8)
	s_waitcnt lgkmcnt(0)
	s_barrier
	s_setprio 1
	s_waitcnt lgkmcnt(0)
	v_mfma_f32_16x16x32_bf16 v[124:127], v[132:135], v[192:195], v[124:127]
	v_mfma_f32_16x16x32_bf16 v[120:123], v[150:153], v[192:195], v[120:123]
	v_mfma_f32_16x16x32_bf16 v[108:111], v[132:135], v[200:203], v[108:111]
	v_mfma_f32_16x16x32_bf16 v[104:107], v[150:153], v[200:203], v[104:107]
	v_mfma_f32_16x16x32_bf16 v[92:95], v[132:135], v[214:217], v[92:95]
	v_mfma_f32_16x16x32_bf16 v[88:91], v[150:153], v[214:217], v[88:91]
	v_mfma_f32_16x16x32_bf16 v[76:79], v[132:135], v[234:237], v[76:79]
	v_mfma_f32_16x16x32_bf16 v[72:75], v[150:153], v[234:237], v[72:75]
	v_mfma_f32_16x16x32_bf16 v[124:127], v[146:149], v[196:199], v[124:127]
	v_mfma_f32_16x16x32_bf16 v[120:123], v[172:175], v[196:199], v[120:123]
	v_mfma_f32_16x16x32_bf16 v[108:111], v[146:149], v[208:211], v[108:111]
	v_mfma_f32_16x16x32_bf16 v[104:107], v[172:175], v[208:211], v[104:107]
	v_mfma_f32_16x16x32_bf16 v[92:95], v[146:149], v[230:233], v[92:95]
	v_mfma_f32_16x16x32_bf16 v[88:91], v[172:175], v[230:233], v[88:91]
	v_mfma_f32_16x16x32_bf16 v[76:79], v[146:149], v[238:241], v[76:79]
	v_mfma_f32_16x16x32_bf16 v[72:75], v[172:175], v[238:241], v[72:75]
	s_setprio 0
	s_setprio 1
	v_mfma_f32_16x16x32_bf16 v[116:119], v[176:179], v[192:195], v[116:119]
	v_mfma_f32_16x16x32_bf16 v[112:115], v[184:187], v[192:195], v[112:115]
	v_mfma_f32_16x16x32_bf16 v[100:103], v[176:179], v[200:203], v[100:103]
	v_mfma_f32_16x16x32_bf16 v[96:99], v[184:187], v[200:203], v[96:99]
	v_mfma_f32_16x16x32_bf16 v[84:87], v[176:179], v[214:217], v[84:87]
	v_mfma_f32_16x16x32_bf16 v[80:83], v[184:187], v[214:217], v[80:83]
	v_mfma_f32_16x16x32_bf16 v[68:71], v[176:179], v[234:237], v[68:71]
	v_mfma_f32_16x16x32_bf16 v[64:67], v[184:187], v[234:237], v[64:67]
	v_mfma_f32_16x16x32_bf16 v[116:119], v[180:183], v[196:199], v[116:119]
	v_mfma_f32_16x16x32_bf16 v[112:115], v[188:191], v[196:199], v[112:115]
	v_mfma_f32_16x16x32_bf16 v[100:103], v[180:183], v[208:211], v[100:103]
	v_mfma_f32_16x16x32_bf16 v[96:99], v[188:191], v[208:211], v[96:99]
	v_mfma_f32_16x16x32_bf16 v[84:87], v[180:183], v[230:233], v[84:87]
	v_mfma_f32_16x16x32_bf16 v[80:83], v[188:191], v[230:233], v[80:83]
	v_mfma_f32_16x16x32_bf16 v[68:71], v[180:183], v[238:241], v[68:71]
	v_mfma_f32_16x16x32_bf16 v[64:67], v[188:191], v[238:241], v[64:67]
	s_setprio 0
	s_barrier
	s_add_i32 s8, s50, s81
	v_lshl_add_u64 v[154:155], s[26:27], 0, v[156:157]
	s_mov_b32 m0, s8
	ds_read_b128 v[192:195], v170 offset:16384
	ds_read_b128 v[196:199], v170 offset:17408
	ds_read_b128 v[200:203], v170 offset:18432
	ds_read_b128 v[208:211], v170 offset:19456
	ds_read_b128 v[214:217], v170 offset:20480
	ds_read_b128 v[230:233], v170 offset:21504
	ds_read_b128 v[234:237], v170 offset:22528
	ds_read_b128 v[238:241], v170 offset:23552
	global_load_lds_dwordx4 v[154:155], off
	s_add_i32 m0, s8, 0x2000
	v_lshl_add_u64 v[204:205], s[26:27], 0, v[140:141]
	s_add_u32 s26, s26, s16
	s_addc_u32 s27, s27, 0
	s_add_i32 s8, s51, s81
	global_load_lds_dwordx4 v[204:205], off
	v_lshl_add_u64 v[206:207], s[26:27], 0, v[156:157]
	s_mov_b32 m0, s8
	v_lshl_add_u64 v[242:243], s[26:27], 0, v[140:141]
	global_load_lds_dwordx4 v[206:207], off
	s_add_i32 m0, s8, 0x2000
	v_lshl_add_u64 v[244:245], s[76:77], 0, v[136:137]
	global_load_lds_dwordx4 v[242:243], off
	s_mov_b32 m0, s83
	s_nop 0
	global_load_lds_dwordx4 v[244:245], off
	v_lshl_add_u64 v[244:245], s[76:77], 0, v[138:139]
	s_mov_b32 m0, s2
	s_nop 0
	global_load_lds_dwordx4 v[244:245], off
	s_waitcnt vmcnt(8)
	s_waitcnt lgkmcnt(0)
	s_barrier
; #define PG8_STAGE(bufoff, gbase, voff) do { _Pragma("unroll") for (int _i = 0; _i < 2; ++_i) \
;         __builtin_amdgcn_global_load_lds((const unsigned*)((const char*)(gbase) + (voff)[_i]), (LAS unsigned*)(lds + (bufoff) + ldsw + _i * 8192), 16, 0, 0); } while (0)
; #define PG8_LDA(dst, b, h) do { _Pragma("unroll") for (int m = 0; m < 4; ++m) _Pragma("unroll") for (int k = 0; k < 2; ++k) dst[m][k] = *(const LAS bf16x8*)(lds + PG8_SA(b, h) + aoff + m * 2048 + k * 1024); } while (0)
; #define PG8_LDB(dst, b, h) do { _Pragma("unroll") for (int n = 0; n < 2; ++n) _Pragma("unroll") for (int k = 0; k < 2; ++k) dst[n][k] = *(const LAS bf16x8*)(lds + PG8_SB(b, h) + boff + n * 2048 + k * 1024); } while (0)
; #define PG8_MMA(ai, bj, At, Bt) do { __builtin_amdgcn_s_setprio(1); _Pragma("unroll") for (int m = 0; m < 4; ++m) _Pragma("unroll") for (int n = 0; n < 2; ++n) _Pragma("unroll") for (int k = 0; k < 2; ++k) \
;         acc[ai][bj][m][n] = __builtin_amdgcn_mfma_f32_16x16x32_bf16(Bt[n][k], At[m][k], acc[ai][bj][m][n], 0, 0, 0); __builtin_amdgcn_s_setprio(0); } while (0)
; #define PG8_WAIT_V(n) asm volatile("s_waitcnt vmcnt(" #n ")" ::: "memory")
; #define PG8_WAIT_L(n) asm volatile("s_waitcnt lgkmcnt(" #n ")" ::: "memory")
; #define PG8_BAR __builtin_amdgcn_s_barrier()
; #define PG8_SCHED __builtin_amdgcn_sched_barrier(0)
;     ...
;             PG8_LDB(B0, 1, 0); PG8_LDB(B1, 1, 1); PG8_SCHED; PG8_LDA(At, 1, 0); PG8_STAGE(PG8_SA(0, 1), a2 + hA, voffA);
;             PG8_WAIT_V(8); PG8_WAIT_L(0); PG8_BAR; PG8_MMA(0, 0, At, B0); PG8_MMA(0, 1, At, B1); PG8_BAR; PG8_SCHED;
;             PG8_LDA(At, 1, 1); PG8_STAGE(PG8_SB(1, 0), b3, voffB); PG8_STAGE(PG8_SB(1, 1), b3 + hB, voffB); PG8_STAGE(PG8_SA(1, 0), a3, voffA);
	s_setprio 1
	s_waitcnt lgkmcnt(0)
	v_mfma_f32_16x16x32_bf16 v[60:63], v[132:135], v[192:195], v[60:63]
	v_mfma_f32_16x16x32_bf16 v[56:59], v[150:153], v[192:195], v[56:59]
	v_mfma_f32_16x16x32_bf16 v[44:47], v[132:135], v[200:203], v[44:47]
	v_mfma_f32_16x16x32_bf16 v[40:43], v[150:153], v[200:203], v[40:43]
	v_mfma_f32_16x16x32_bf16 v[28:31], v[132:135], v[214:217], v[28:31]
	v_mfma_f32_16x16x32_bf16 v[24:27], v[150:153], v[214:217], v[24:27]
	v_mfma_f32_16x16x32_bf16 v[12:15], v[132:135], v[234:237], v[12:15]
	v_mfma_f32_16x16x32_bf16 v[8:11], v[150:153], v[234:237], v[8:11]
	v_mfma_f32_16x16x32_bf16 v[60:63], v[146:149], v[196:199], v[60:63]
	v_mfma_f32_16x16x32_bf16 v[56:59], v[172:175], v[196:199], v[56:59]
	v_mfma_f32_16x16x32_bf16 v[44:47], v[146:149], v[208:211], v[44:47]
	v_mfma_f32_16x16x32_bf16 v[40:43], v[172:175], v[208:211], v[40:43]
	v_mfma_f32_16x16x32_bf16 v[28:31], v[146:149], v[230:233], v[28:31]
	v_mfma_f32_16x16x32_bf16 v[24:27], v[172:175], v[230:233], v[24:27]
	v_mfma_f32_16x16x32_bf16 v[12:15], v[146:149], v[238:241], v[12:15]
	v_mfma_f32_16x16x32_bf16 v[8:11], v[172:175], v[238:241], v[8:11]
	s_setprio 0
	s_setprio 1
	v_mfma_f32_16x16x32_bf16 v[52:55], v[176:179], v[192:195], v[52:55]
	v_mfma_f32_16x16x32_bf16 v[48:51], v[184:187], v[192:195], v[48:51]
	v_mfma_f32_16x16x32_bf16 v[36:39], v[176:179], v[200:203], v[36:39]
	v_mfma_f32_16x16x32_bf16 v[32:35], v[184:187], v[200:203], v[32:35]
	v_mfma_f32_16x16x32_bf16 v[20:23], v[176:179], v[214:217], v[20:23]
	v_mfma_f32_16x16x32_bf16 v[16:19], v[184:187], v[214:217], v[16:19]
	v_mfma_f32_16x16x32_bf16 v[4:7], v[176:179], v[234:237], v[4:7]
	v_mfma_f32_16x16x32_bf16 v[0:3], v[184:187], v[234:237], v[0:3]
	v_mfma_f32_16x16x32_bf16 v[52:55], v[180:183], v[196:199], v[52:55]
	v_mfma_f32_16x16x32_bf16 v[48:51], v[188:191], v[196:199], v[48:51]
	v_mfma_f32_16x16x32_bf16 v[36:39], v[180:183], v[208:211], v[36:39]
	v_mfma_f32_16x16x32_bf16 v[32:35], v[188:191], v[208:211], v[32:35]
	v_mfma_f32_16x16x32_bf16 v[20:23], v[180:183], v[230:233], v[20:23]
	v_mfma_f32_16x16x32_bf16 v[16:19], v[188:191], v[230:233], v[16:19]
	v_mfma_f32_16x16x32_bf16 v[4:7], v[180:183], v[238:241], v[4:7]
	v_mfma_f32_16x16x32_bf16 v[0:3], v[188:191], v[238:241], v[0:3]
	s_setprio 0
	s_barrier
	s_add_i32 s8, 0, 0x18000
	v_add_u32_e32 v171, s8, v168
	s_add_i32 s9, 0, 0x1c000
	ds_read_b128 v[132:135], v171
	ds_read_b128 v[146:149], v171 offset:1024
	ds_read_b128 v[150:153], v171 offset:2048
	ds_read_b128 v[172:175], v171 offset:3072
	v_add_u32_e32 v171, s9, v168
	ds_read_b128 v[176:179], v171
	ds_read_b128 v[180:183], v171 offset:1024
	ds_read_b128 v[184:187], v171 offset:2048
	ds_read_b128 v[188:191], v171 offset:3072
	s_add_u32 s26, s76, s16
	s_addc_u32 s27, s77, 0
	s_mov_b32 m0, s3
	v_lshl_add_u64 v[244:245], s[26:27], 0, v[136:137]
	ds_read_b128 v[192:195], v170 offset:32768
	ds_read_b128 v[196:199], v170 offset:33792
	ds_read_b128 v[200:203], v170 offset:34816
	ds_read_b128 v[208:211], v170 offset:35840
	ds_read_b128 v[214:217], v170 offset:36864
	ds_read_b128 v[230:233], v170 offset:37888
	ds_read_b128 v[234:237], v170 offset:38912
	ds_read_b128 v[238:241], v170 offset:39936
	global_load_lds_dwordx4 v[244:245], off
	v_lshl_add_u64 v[244:245], s[26:27], 0, v[138:139]
	s_mov_b32 m0, s0
	s_nop 0
	global_load_lds_dwordx4 v[244:245], off
	s_waitcnt vmcnt(8)
	s_waitcnt lgkmcnt(0)
	s_barrier
	s_setprio 1
	s_waitcnt lgkmcnt(0)
	v_mfma_f32_16x16x32_bf16 v[124:127], v[132:135], v[192:195], v[124:127]
	v_mfma_f32_16x16x32_bf16 v[120:123], v[150:153], v[192:195], v[120:123]
	v_mfma_f32_16x16x32_bf16 v[108:111], v[132:135], v[200:203], v[108:111]
	v_mfma_f32_16x16x32_bf16 v[104:107], v[150:153], v[200:203], v[104:107]
	v_mfma_f32_16x16x32_bf16 v[92:95], v[132:135], v[214:217], v[92:95]
	v_mfma_f32_16x16x32_bf16 v[88:91], v[150:153], v[214:217], v[88:91]
	v_mfma_f32_16x16x32_bf16 v[76:79], v[132:135], v[234:237], v[76:79]
	v_mfma_f32_16x16x32_bf16 v[72:75], v[150:153], v[234:237], v[72:75]
	v_mfma_f32_16x16x32_bf16 v[124:127], v[146:149], v[196:199], v[124:127]
	v_mfma_f32_16x16x32_bf16 v[120:123], v[172:175], v[196:199], v[120:123]
	v_mfma_f32_16x16x32_bf16 v[108:111], v[146:149], v[208:211], v[108:111]
	v_mfma_f32_16x16x32_bf16 v[104:107], v[172:175], v[208:211], v[104:107]
	v_mfma_f32_16x16x32_bf16 v[92:95], v[146:149], v[230:233], v[92:95]
	v_mfma_f32_16x16x32_bf16 v[88:91], v[172:175], v[230:233], v[88:91]
	v_mfma_f32_16x16x32_bf16 v[76:79], v[146:149], v[238:241], v[76:79]
	v_mfma_f32_16x16x32_bf16 v[72:75], v[172:175], v[238:241], v[72:75]
	s_setprio 0
	s_setprio 1
	v_mfma_f32_16x16x32_bf16 v[116:119], v[176:179], v[192:195], v[116:119]
	v_mfma_f32_16x16x32_bf16 v[112:115], v[184:187], v[192:195], v[112:115]
	v_mfma_f32_16x16x32_bf16 v[100:103], v[176:179], v[200:203], v[100:103]
	v_mfma_f32_16x16x32_bf16 v[96:99], v[184:187], v[200:203], v[96:99]
	v_mfma_f32_16x16x32_bf16 v[84:87], v[176:179], v[214:217], v[84:87]
	v_mfma_f32_16x16x32_bf16 v[80:83], v[184:187], v[214:217], v[80:83]
	v_mfma_f32_16x16x32_bf16 v[68:71], v[176:179], v[234:237], v[68:71]
	v_mfma_f32_16x16x32_bf16 v[64:67], v[184:187], v[234:237], v[64:67]
	v_mfma_f32_16x16x32_bf16 v[116:119], v[180:183], v[196:199], v[116:119]
	v_mfma_f32_16x16x32_bf16 v[112:115], v[188:191], v[196:199], v[112:115]
	v_mfma_f32_16x16x32_bf16 v[100:103], v[180:183], v[208:211], v[100:103]
	v_mfma_f32_16x16x32_bf16 v[96:99], v[188:191], v[208:211], v[96:99]
	v_mfma_f32_16x16x32_bf16 v[84:87], v[180:183], v[230:233], v[84:87]
	v_mfma_f32_16x16x32_bf16 v[80:83], v[188:191], v[230:233], v[80:83]
	v_mfma_f32_16x16x32_bf16 v[68:71], v[180:183], v[238:241], v[68:71]
	v_mfma_f32_16x16x32_bf16 v[64:67], v[188:191], v[238:241], v[64:67]
	s_setprio 0
	s_barrier
; #define PG8_STAGE(bufoff, gbase, voff) do { _Pragma("unroll") for (int _i = 0; _i < 2; ++_i) \
;         __builtin_amdgcn_global_load_lds((const unsigned*)((const char*)(gbase) + (voff)[_i]), (LAS unsigned*)(lds + (bufoff) + ldsw + _i * 8192), 16, 0, 0); } while (0)
; #define PG8_LDA(dst, b, h) do { _Pragma("unroll") for (int m = 0; m < 4; ++m) _Pragma("unroll") for (int k = 0; k < 2; ++k) dst[m][k] = *(const LAS bf16x8*)(lds + PG8_SA(b, h) + aoff + m * 2048 + k * 1024); } while (0)
; #define PG8_MMA(ai, bj, At, Bt) do { __builtin_amdgcn_s_setprio(1); _Pragma("unroll") for (int m = 0; m < 4; ++m) _Pragma("unroll") for (int n = 0; n < 2; ++n) _Pragma("unroll") for (int k = 0; k < 2; ++k) \
;         acc[ai][bj][m][n] = __builtin_amdgcn_mfma_f32_16x16x32_bf16(Bt[n][k], At[m][k], acc[ai][bj][m][n], 0, 0, 0); __builtin_amdgcn_s_setprio(0); } while (0)
; #define PG8_WAIT_V(n) asm volatile("s_waitcnt vmcnt(" #n ")" ::: "memory")
; #define PG8_WAIT_L(n) asm volatile("s_waitcnt lgkmcnt(" #n ")" ::: "memory")
; #define PG8_BAR __builtin_amdgcn_s_barrier()
; #define PG8_SCHED __builtin_amdgcn_sched_barrier(0)
;     ...
;             PG8_LDA(At, 1, 1); PG8_STAGE(PG8_SB(1, 0), b3, voffB); PG8_STAGE(PG8_SB(1, 1), b3 + hB, voffB); PG8_STAGE(PG8_SA(1, 0), a3, voffA);
;             PG8_WAIT_V(8); PG8_WAIT_L(0); PG8_BAR; PG8_MMA(1, 0, At, B0); PG8_MMA(1, 1, At, B1); PG8_BAR; PG8_SCHED;
	s_add_i32 s8, s8, s81
	v_lshl_add_u64 v[154:155], v[154:155], 0, s[38:39]
	s_mov_b32 m0, s8
	ds_read_b128 v[192:195], v170 offset:49152
	ds_read_b128 v[196:199], v170 offset:50176
	ds_read_b128 v[200:203], v170 offset:51200
	ds_read_b128 v[208:211], v170 offset:52224
	ds_read_b128 v[214:217], v170 offset:53248
	ds_read_b128 v[230:233], v170 offset:54272
	ds_read_b128 v[234:237], v170 offset:55296
	ds_read_b128 v[238:241], v170 offset:56320
	global_load_lds_dwordx4 v[154:155], off
	v_lshl_add_u64 v[154:155], v[204:205], 0, s[38:39]
	s_add_i32 m0, s8, 0x2000
	s_add_i32 s8, s9, s81
	global_load_lds_dwordx4 v[154:155], off
	v_lshl_add_u64 v[154:155], v[206:207], 0, s[38:39]
	s_mov_b32 m0, s8
	s_nop 0
	global_load_lds_dwordx4 v[154:155], off
	v_lshl_add_u64 v[154:155], v[242:243], 0, s[38:39]
	s_add_i32 m0, s8, 0x2000
	s_nop 0
	global_load_lds_dwordx4 v[154:155], off
	v_lshl_add_u64 v[154:155], s[74:75], 0, v[136:137]
	s_mov_b32 m0, s1
	s_nop 0
	global_load_lds_dwordx4 v[154:155], off
	v_lshl_add_u64 v[154:155], s[74:75], 0, v[138:139]
	s_mov_b32 m0, s54
	s_nop 0
	global_load_lds_dwordx4 v[154:155], off
	s_waitcnt vmcnt(8)
	s_waitcnt lgkmcnt(0)
	s_barrier
	s_setprio 1
	s_waitcnt lgkmcnt(0)
	v_mfma_f32_16x16x32_bf16 v[60:63], v[132:135], v[192:195], v[60:63]
	v_mfma_f32_16x16x32_bf16 v[56:59], v[150:153], v[192:195], v[56:59]
	v_mfma_f32_16x16x32_bf16 v[44:47], v[132:135], v[200:203], v[44:47]
	v_mfma_f32_16x16x32_bf16 v[40:43], v[150:153], v[200:203], v[40:43]
	v_mfma_f32_16x16x32_bf16 v[28:31], v[132:135], v[214:217], v[28:31]
	v_mfma_f32_16x16x32_bf16 v[24:27], v[150:153], v[214:217], v[24:27]
	v_mfma_f32_16x16x32_bf16 v[12:15], v[132:135], v[234:237], v[12:15]
	v_mfma_f32_16x16x32_bf16 v[8:11], v[150:153], v[234:237], v[8:11]
	v_mfma_f32_16x16x32_bf16 v[60:63], v[146:149], v[196:199], v[60:63]
	v_mfma_f32_16x16x32_bf16 v[56:59], v[172:175], v[196:199], v[56:59]
	v_mfma_f32_16x16x32_bf16 v[44:47], v[146:149], v[208:211], v[44:47]
	v_mfma_f32_16x16x32_bf16 v[40:43], v[172:175], v[208:211], v[40:43]
	v_mfma_f32_16x16x32_bf16 v[28:31], v[146:149], v[230:233], v[28:31]
	v_mfma_f32_16x16x32_bf16 v[24:27], v[172:175], v[230:233], v[24:27]
	v_mfma_f32_16x16x32_bf16 v[12:15], v[146:149], v[238:241], v[12:15]
	v_mfma_f32_16x16x32_bf16 v[8:11], v[172:175], v[238:241], v[8:11]
	s_setprio 0
	s_setprio 1
	v_mfma_f32_16x16x32_bf16 v[52:55], v[176:179], v[192:195], v[52:55]
	v_mfma_f32_16x16x32_bf16 v[48:51], v[184:187], v[192:195], v[48:51]
	v_mfma_f32_16x16x32_bf16 v[36:39], v[176:179], v[200:203], v[36:39]
	v_mfma_f32_16x16x32_bf16 v[32:35], v[184:187], v[200:203], v[32:35]
	v_mfma_f32_16x16x32_bf16 v[20:23], v[176:179], v[214:217], v[20:23]
	v_mfma_f32_16x16x32_bf16 v[16:19], v[184:187], v[214:217], v[16:19]
	v_mfma_f32_16x16x32_bf16 v[4:7], v[176:179], v[234:237], v[4:7]
	v_mfma_f32_16x16x32_bf16 v[0:3], v[184:187], v[234:237], v[0:3]
	v_mfma_f32_16x16x32_bf16 v[52:55], v[180:183], v[196:199], v[52:55]
	v_mfma_f32_16x16x32_bf16 v[48:51], v[188:191], v[196:199], v[48:51]
	v_mfma_f32_16x16x32_bf16 v[36:39], v[180:183], v[208:211], v[36:39]
	v_mfma_f32_16x16x32_bf16 v[32:35], v[188:191], v[208:211], v[32:35]
	v_mfma_f32_16x16x32_bf16 v[20:23], v[180:183], v[230:233], v[20:23]
	v_mfma_f32_16x16x32_bf16 v[16:19], v[188:191], v[230:233], v[16:19]
	v_mfma_f32_16x16x32_bf16 v[4:7], v[180:183], v[238:241], v[4:7]
	v_mfma_f32_16x16x32_bf16 v[0:3], v[188:191], v[238:241], v[0:3]
	s_setprio 0
	s_barrier
	s_add_u32 vcc_lo, vcc_lo, 0x100
	s_addc_u32 vcc_hi, vcc_hi, 0
	s_cmp_ge_u32 s6, s4
	s_mov_b32 s74, s6
	s_cbranch_scc0 .LBB0_364
	s_and_b64 vcc, exec, s[30:31]
	s_cbranch_vccz .LBB0_367
	s_barrier
